# plus: P1-tail p->bf16 conversion with all 16 loads in flight
# baseline (speedup 1.0000x reference)
; #define LAS __attribute__((address_space(3)))
; __device__ __forceinline__ unsigned pk2(float lo, float hi) { return cvtpk_(lo, hi); }
; #define INF(k) ((const float*)LDP(k))
; __global__ void __launch_bounds__(512, 2) fwd_megakernel(Args a) {
;     ...
;         const int rem = ((T / 256) * (INW / 256)) % G;
;         if (rem == 0 || bid >= rem) { PH_IDS (void)gw;
;             LAS float* scr = (LAS float*)(lds + wave * 16384);
;             const int first = (rem == 0 ? bid : bid - rem) * 8 + wave, step = (rem == 0 ? G : G - rem) * 8;
;             {
;                 const int gt2 = (rem == 0 ? bid : bid - rem) * 512 + tid, ngt2 = (rem == 0 ? G : G - rem) * 512;
;                 for (int i = gt2; i < T * 64; i += ngt2) { const f32x4 v = ((const f32x4*)INF(I_P))[i]; u32x2 w; w.x = pk2(v[0], v[1]); w.y = pk2(v[2], v[3]); ((u32x2*)PB)[i] = w; }
.LBB0_132:
	s_add_u32 s62, s52, 0x5b00000
	s_addc_u32 s63, s53, 0
	s_add_u32 s70, s52, 0x100000
	s_addc_u32 s71, s53, 0
	s_add_u32 s60, s52, 0x5300000
	s_addc_u32 s61, s53, 0
	s_add_u32 s68, s52, 0x900000
	s_addc_u32 s69, s53, 0
	s_add_u32 s66, s52, 0x3d00000
	s_addc_u32 s67, s53, 0
	s_abs_i32 s0, s54
	v_cvt_f32_u32_e32 v0, s0
	s_sub_i32 s1, 0, s0
	v_rcp_iflag_f32_e32 v0, v0
	s_nop 0
	v_mul_f32_e32 v0, 0x4f7ffffe, v0
	v_cvt_u32_f32_e32 v0, v0
	s_nop 0
	v_readfirstlane_b32 s2, v0
	s_mul_i32 s1, s1, s2
	s_mul_hi_u32 s1, s2, s1
	s_add_i32 s2, s2, s1
	s_mul_hi_u32 s1, s2, 0x980
	s_mul_i32 s1, s1, s0
	s_sub_i32 s1, 0x980, s1
	s_sub_i32 s2, s1, s0
	s_cmp_ge_u32 s1, s0
	s_cselect_b32 s1, s2, s1
	s_sub_i32 s2, s1, s0
	s_cmp_ge_u32 s1, s0
	s_cselect_b32 s0, s2, s1
	s_cmp_lg_u32 s0, 0
	s_cselect_b64 s[2:3], -1, 0
	s_cmp_lt_i32 s33, s0
	s_cselect_b64 s[4:5], -1, 0
	s_and_b64 s[2:3], s[2:3], s[4:5]
	s_and_b64 vcc, exec, s[2:3]
	s_cbranch_vccnz .LBB0_171
	v_mbcnt_lo_u32_b32 v0, -1, 0
	v_mbcnt_hi_u32_b32 v0, -1, v0
	s_sub_i32 s2, s33, s0
	v_add_u32_e32 v8, s84, v0
	s_sub_i32 s12, s54, s0
	v_lshl_add_u32 v0, s2, 9, v8
	s_mov_b32 s0, 0x100000
	v_readfirstlane_b32 s3, v8
	v_cmp_gt_i32_e32 vcc, s0, v0
	s_and_saveexec_b64 s[0:1], vcc
	s_cbranch_execz .LBB0_136
	s_add_i32 s5, 0, 0x23c48
	v_mov_b32_e32 v1, s5
	ds_read_b64 v[2:3], v1
	s_lshl_b32 s4, s12, 9
	v_ashrrev_i32_e32 v1, 31, v0
	s_ashr_i32 s5, s4, 31
	v_lshl_add_u64 v[6:7], v[0:1], 3, s[52:53]
	s_mov_b64 s[8:9], 0x9c00000
	v_lshlrev_b64 v[4:5], 4, v[0:1]
	s_lshl_b64 s[6:7], s[4:5], 4
	v_lshl_add_u64 v[6:7], v[6:7], 0, s[8:9]
	s_lshl_b64 s[8:9], s[4:5], 3
	s_mov_b64 s[10:11], 0
	s_mov_b32 s5, 0xfffff
	s_cmp_eq_u32 s4, 0x10000
	s_cbranch_scc0 .LBB0_135
	s_waitcnt lgkmcnt(0)
	v_readfirstlane_b32 s15, v3
	v_readfirstlane_b32 s14, v2
	s_nop 1
	v_lshl_add_u64 v[88:89], s[14:15], 0, v[4:5]
	global_load_dwordx4 v[92:95], v[88:89], off
	v_lshl_add_u64 v[88:89], v[88:89], 0, s[6:7]
	global_load_dwordx4 v[96:99], v[88:89], off
	v_lshl_add_u64 v[88:89], v[88:89], 0, s[6:7]
	global_load_dwordx4 v[100:103], v[88:89], off
	v_lshl_add_u64 v[88:89], v[88:89], 0, s[6:7]
	global_load_dwordx4 v[104:107], v[88:89], off
	v_lshl_add_u64 v[88:89], v[88:89], 0, s[6:7]
	global_load_dwordx4 v[108:111], v[88:89], off
	v_lshl_add_u64 v[88:89], v[88:89], 0, s[6:7]
	global_load_dwordx4 v[112:115], v[88:89], off
	v_lshl_add_u64 v[88:89], v[88:89], 0, s[6:7]
	global_load_dwordx4 v[116:119], v[88:89], off
	v_lshl_add_u64 v[88:89], v[88:89], 0, s[6:7]
	global_load_dwordx4 v[120:123], v[88:89], off
	v_lshl_add_u64 v[88:89], v[88:89], 0, s[6:7]
	global_load_dwordx4 v[124:127], v[88:89], off
	v_lshl_add_u64 v[88:89], v[88:89], 0, s[6:7]
	global_load_dwordx4 v[128:131], v[88:89], off
	v_lshl_add_u64 v[88:89], v[88:89], 0, s[6:7]
	global_load_dwordx4 v[132:135], v[88:89], off
	v_lshl_add_u64 v[88:89], v[88:89], 0, s[6:7]
	global_load_dwordx4 v[136:139], v[88:89], off
	v_lshl_add_u64 v[88:89], v[88:89], 0, s[6:7]
	global_load_dwordx4 v[140:143], v[88:89], off
	v_lshl_add_u64 v[88:89], v[88:89], 0, s[6:7]
	global_load_dwordx4 v[144:147], v[88:89], off
	v_lshl_add_u64 v[88:89], v[88:89], 0, s[6:7]
	global_load_dwordx4 v[148:151], v[88:89], off
	v_lshl_add_u64 v[88:89], v[88:89], 0, s[6:7]
	global_load_dwordx4 v[152:155], v[88:89], off
	s_waitcnt vmcnt(15)
	v_cvt_pk_bf16_f32 v92, v92, v93
	v_cvt_pk_bf16_f32 v93, v94, v95
	global_store_dwordx2 v[6:7], v[92:93], off
	v_lshl_add_u64 v[6:7], v[6:7], 0, s[8:9]
	s_waitcnt vmcnt(15)
	v_cvt_pk_bf16_f32 v96, v96, v97
	v_cvt_pk_bf16_f32 v97, v98, v99
	global_store_dwordx2 v[6:7], v[96:97], off
	v_lshl_add_u64 v[6:7], v[6:7], 0, s[8:9]
	s_waitcnt vmcnt(15)
	v_cvt_pk_bf16_f32 v100, v100, v101
	v_cvt_pk_bf16_f32 v101, v102, v103
	global_store_dwordx2 v[6:7], v[100:101], off
	v_lshl_add_u64 v[6:7], v[6:7], 0, s[8:9]
	s_waitcnt vmcnt(15)
	v_cvt_pk_bf16_f32 v104, v104, v105
	v_cvt_pk_bf16_f32 v105, v106, v107
	global_store_dwordx2 v[6:7], v[104:105], off
	v_lshl_add_u64 v[6:7], v[6:7], 0, s[8:9]
	s_waitcnt vmcnt(15)
	v_cvt_pk_bf16_f32 v108, v108, v109
	v_cvt_pk_bf16_f32 v109, v110, v111
	global_store_dwordx2 v[6:7], v[108:109], off
	v_lshl_add_u64 v[6:7], v[6:7], 0, s[8:9]
	s_waitcnt vmcnt(15)
	v_cvt_pk_bf16_f32 v112, v112, v113
	v_cvt_pk_bf16_f32 v113, v114, v115
	global_store_dwordx2 v[6:7], v[112:113], off
	v_lshl_add_u64 v[6:7], v[6:7], 0, s[8:9]
	s_waitcnt vmcnt(15)
	v_cvt_pk_bf16_f32 v116, v116, v117
	v_cvt_pk_bf16_f32 v117, v118, v119
	global_store_dwordx2 v[6:7], v[116:117], off
	v_lshl_add_u64 v[6:7], v[6:7], 0, s[8:9]
	s_waitcnt vmcnt(15)
	v_cvt_pk_bf16_f32 v120, v120, v121
	v_cvt_pk_bf16_f32 v121, v122, v123
	global_store_dwordx2 v[6:7], v[120:121], off
	v_lshl_add_u64 v[6:7], v[6:7], 0, s[8:9]
	s_waitcnt vmcnt(15)
	v_cvt_pk_bf16_f32 v124, v124, v125
	v_cvt_pk_bf16_f32 v125, v126, v127
	global_store_dwordx2 v[6:7], v[124:125], off
	v_lshl_add_u64 v[6:7], v[6:7], 0, s[8:9]
	s_waitcnt vmcnt(15)
	v_cvt_pk_bf16_f32 v128, v128, v129
	v_cvt_pk_bf16_f32 v129, v130, v131
	global_store_dwordx2 v[6:7], v[128:129], off
	v_lshl_add_u64 v[6:7], v[6:7], 0, s[8:9]
	s_waitcnt vmcnt(15)
	v_cvt_pk_bf16_f32 v132, v132, v133
	v_cvt_pk_bf16_f32 v133, v134, v135
	global_store_dwordx2 v[6:7], v[132:133], off
	v_lshl_add_u64 v[6:7], v[6:7], 0, s[8:9]
	s_waitcnt vmcnt(15)
	v_cvt_pk_bf16_f32 v136, v136, v137
	v_cvt_pk_bf16_f32 v137, v138, v139
	global_store_dwordx2 v[6:7], v[136:137], off
	v_lshl_add_u64 v[6:7], v[6:7], 0, s[8:9]
	s_waitcnt vmcnt(15)
	v_cvt_pk_bf16_f32 v140, v140, v141
	v_cvt_pk_bf16_f32 v141, v142, v143
	global_store_dwordx2 v[6:7], v[140:141], off
	v_lshl_add_u64 v[6:7], v[6:7], 0, s[8:9]
	s_waitcnt vmcnt(15)
	v_cvt_pk_bf16_f32 v144, v144, v145
	v_cvt_pk_bf16_f32 v145, v146, v147
	global_store_dwordx2 v[6:7], v[144:145], off
	v_lshl_add_u64 v[6:7], v[6:7], 0, s[8:9]
	s_waitcnt vmcnt(15)
	v_cvt_pk_bf16_f32 v148, v148, v149
	v_cvt_pk_bf16_f32 v149, v150, v151
	global_store_dwordx2 v[6:7], v[148:149], off
	v_lshl_add_u64 v[6:7], v[6:7], 0, s[8:9]
	s_waitcnt vmcnt(15)
	v_cvt_pk_bf16_f32 v152, v152, v153
	v_cvt_pk_bf16_f32 v153, v154, v155
	global_store_dwordx2 v[6:7], v[152:153], off
	s_branch .LBB0_136
